# SSD conv stage: single vmcnt(4) instead of the vmcnt(7..0) ladder that also waited for the previous chunk's output stores (first chunk keeps vmcnt(0))
# speedup vs baseline: 1.0005x; 1.0005x over previous
.LBB0_322:
	s_or_b64 exec, exec, s[40:41]
	s_waitcnt lgkmcnt(0)
	s_barrier
	ds_read_b128 v[34:37], v219
	ds_read_b128 v[18:21], v219 offset:16
	ds_read_b64 v[22:23], v219 offset:32
	v_lshlrev_b32_e32 v38, 16, v190
	v_and_b32_e32 v39, 0xffff0000, v190
	s_waitcnt lgkmcnt(2)
	v_mov_b32_e32 v32, v34
	s_waitcnt lgkmcnt(1)
	v_mov_b32_e32 v33, v18
	v_lshlrev_b32_e32 v40, 16, v192
	v_and_b32_e32 v41, 0xffff0000, v192
	s_waitcnt lgkmcnt(0)
	v_pk_fma_f32 v[38:39], v[32:33], v[38:39], v[22:23]
	v_mov_b32_e32 v18, v35
	v_lshlrev_b32_e32 v42, 16, v252
	v_and_b32_e32 v43, 0xffff0000, v252
	v_pk_fma_f32 v[38:39], v[18:19], v[40:41], v[38:39]
	v_mov_b32_e32 v34, v36
	v_mov_b32_e32 v35, v20
	s_waitcnt vmcnt(8)
	v_lshlrev_b32_e32 v44, 16, v251
	v_and_b32_e32 v45, 0xffff0000, v251
	v_pk_fma_f32 v[38:39], v[34:35], v[42:43], v[38:39]
	v_mov_b32_e32 v20, v37
	v_pk_fma_f32 v[36:37], v[20:21], v[44:45], v[38:39]
	s_mov_b32 s40, 0xbfb8aa3b
	v_pk_mul_f32 v[38:39], v[36:37], s[40:41] op_sel_hi:[1,0]
	v_lshlrev_b32_e32 v46, 16, v0
	v_exp_f32_e32 v38, v38
	v_exp_f32_e32 v39, v39
	v_and_b32_e32 v47, 0xffff0000, v0
	v_lshlrev_b32_e32 v48, 16, v123
	v_and_b32_e32 v49, 0xffff0000, v123
	v_pk_add_f32 v[38:39], v[38:39], 1.0 op_sel_hi:[1,0]
	v_lshlrev_b32_e32 v82, 16, v246
	v_rcp_f32_e32 v38, v38
	v_rcp_f32_e32 v39, v39
	v_and_b32_e32 v83, 0xffff0000, v246
	v_lshlrev_b32_e32 v24, 16, v247
	v_and_b32_e32 v25, 0xffff0000, v247
	v_pk_mul_f32 v[36:37], v[36:37], v[38:39]
	ds_read2_b32 v[38:39], v147 offset1:1
	ds_read2_b32 v[84:85], v147 offset0:2 offset1:3
	ds_read2_b32 v[86:87], v147 offset0:4 offset1:5
	v_cvt_pk_bf16_f32 v88, v36, v37
	v_lshlrev_b32_e32 v28, 16, v248
	s_waitcnt lgkmcnt(2)
	v_pk_mul_f32 v[36:37], v[38:39], v[36:37] op_sel_hi:[0,1]
	v_cvt_pk_bf16_f32 v36, v36, v37
	ds_write2_b32 v220, v88, v36 offset1:32
	v_pk_fma_f32 v[36:37], v[32:33], v[40:41], v[22:23]
	v_mov_b32_e32 v38, v39
	v_pk_fma_f32 v[36:37], v[18:19], v[42:43], v[36:37]
	v_and_b32_e32 v29, 0xffff0000, v248
	v_pk_fma_f32 v[36:37], v[34:35], v[44:45], v[36:37]
	v_lshlrev_b32_e32 v30, 16, v249
	v_pk_fma_f32 v[36:37], v[20:21], v[46:47], v[36:37]
	v_and_b32_e32 v31, 0xffff0000, v249
	v_pk_mul_f32 v[40:41], v[36:37], s[40:41] op_sel_hi:[1,0]
	v_lshlrev_b32_e32 v26, 16, v250
	v_exp_f32_e32 v40, v40
	v_exp_f32_e32 v41, v41
	v_and_b32_e32 v27, 0xffff0000, v250
	s_add_i32 s33, s44, 1
	s_cmp_lg_u32 s44, 31
	v_pk_add_f32 v[40:41], v[40:41], 1.0 op_sel_hi:[1,0]
	s_nop 0
	v_rcp_f32_e32 v40, v40
	v_rcp_f32_e32 v41, v41
	s_nop 0
	v_pk_mul_f32 v[36:37], v[36:37], v[40:41]
	s_nop 0
	v_cvt_pk_bf16_f32 v40, v36, v37
	v_pk_mul_f32 v[36:37], v[38:39], v[36:37] op_sel_hi:[0,1]
	v_cvt_pk_bf16_f32 v36, v36, v37
	ds_write2_b32 v220, v40, v36 offset0:68 offset1:100
	v_pk_fma_f32 v[36:37], v[32:33], v[42:43], v[22:23]
	s_nop 0
	v_pk_fma_f32 v[36:37], v[18:19], v[44:45], v[36:37]
	s_nop 0
	v_pk_fma_f32 v[36:37], v[34:35], v[46:47], v[36:37]
	s_nop 0
	v_pk_fma_f32 v[36:37], v[20:21], v[48:49], v[36:37]
	s_nop 0
	v_pk_mul_f32 v[38:39], v[36:37], s[40:41] op_sel_hi:[1,0]
	s_nop 0
	v_exp_f32_e32 v38, v38
	v_exp_f32_e32 v39, v39
	s_nop 0
	v_pk_add_f32 v[38:39], v[38:39], 1.0 op_sel_hi:[1,0]
	s_nop 0
	v_rcp_f32_e32 v38, v38
	v_rcp_f32_e32 v39, v39
	s_nop 0
	v_pk_mul_f32 v[36:37], v[36:37], v[38:39]
	s_nop 0
	v_cvt_pk_bf16_f32 v38, v36, v37
	s_waitcnt lgkmcnt(3)
	v_pk_mul_f32 v[36:37], v[84:85], v[36:37] op_sel_hi:[0,1]
	v_cvt_pk_bf16_f32 v36, v36, v37
	ds_write2_b32 v220, v38, v36 offset0:136 offset1:168
	v_pk_fma_f32 v[36:37], v[32:33], v[44:45], v[22:23]
	s_nop 0
	v_pk_fma_f32 v[36:37], v[18:19], v[46:47], v[36:37]
	s_nop 0
	v_pk_fma_f32 v[36:37], v[34:35], v[48:49], v[36:37]
	s_nop 0
	v_pk_fma_f32 v[36:37], v[20:21], v[82:83], v[36:37]
	s_nop 0
	v_pk_mul_f32 v[38:39], v[36:37], s[40:41] op_sel_hi:[1,0]
	s_nop 0
	v_exp_f32_e32 v38, v38
	v_exp_f32_e32 v39, v39
	s_nop 0
	v_pk_add_f32 v[38:39], v[38:39], 1.0 op_sel_hi:[1,0]
	s_nop 0
	v_rcp_f32_e32 v38, v38
	v_rcp_f32_e32 v39, v39
	s_nop 0
	v_pk_mul_f32 v[36:37], v[36:37], v[38:39]
	v_mov_b32_e32 v38, v85
	v_cvt_pk_bf16_f32 v39, v36, v37
	s_nop 0
	v_pk_mul_f32 v[36:37], v[36:37], v[38:39] op_sel_hi:[1,0]
	s_nop 0
	v_cvt_pk_bf16_f32 v36, v36, v37
	ds_write2_b32 v220, v39, v36 offset0:204 offset1:236
	v_pk_fma_f32 v[36:37], v[32:33], v[46:47], v[22:23]
	s_nop 0
	v_pk_fma_f32 v[36:37], v[18:19], v[48:49], v[36:37]
	s_nop 0
	v_pk_fma_f32 v[36:37], v[34:35], v[82:83], v[36:37]
	s_nop 0
	v_pk_fma_f32 v[36:37], v[20:21], v[24:25], v[36:37]
	s_nop 0
	v_pk_mul_f32 v[38:39], v[36:37], s[40:41] op_sel_hi:[1,0]
	s_nop 0
	v_exp_f32_e32 v38, v38
	v_exp_f32_e32 v39, v39
	s_nop 0
	v_pk_add_f32 v[38:39], v[38:39], 1.0 op_sel_hi:[1,0]
	s_nop 0
	v_rcp_f32_e32 v38, v38
	v_rcp_f32_e32 v39, v39
	s_nop 0
	v_pk_mul_f32 v[36:37], v[36:37], v[38:39]
	s_nop 0
	v_cvt_pk_bf16_f32 v39, v36, v37
	s_waitcnt lgkmcnt(4)
	v_pk_mul_f32 v[36:37], v[36:37], v[86:87] op_sel_hi:[1,0]
	v_add_u32_e32 v38, 0x400, v220
	v_cvt_pk_bf16_f32 v36, v36, v37
	ds_write2_b32 v38, v39, v36 offset0:16 offset1:48
	v_pk_fma_f32 v[36:37], v[32:33], v[48:49], v[22:23]
	s_nop 0
	v_pk_fma_f32 v[36:37], v[18:19], v[82:83], v[36:37]
	s_nop 0
	v_pk_fma_f32 v[36:37], v[34:35], v[24:25], v[36:37]
	s_nop 0
	v_pk_fma_f32 v[36:37], v[20:21], v[28:29], v[36:37]
	s_nop 0
	v_pk_mul_f32 v[40:41], v[36:37], s[40:41] op_sel_hi:[1,0]
	s_nop 0
	v_exp_f32_e32 v40, v40
	v_exp_f32_e32 v41, v41
	s_nop 0
	v_pk_add_f32 v[40:41], v[40:41], 1.0 op_sel_hi:[1,0]
	s_nop 0
	v_rcp_f32_e32 v40, v40
	v_rcp_f32_e32 v41, v41
	s_nop 0
	v_pk_mul_f32 v[36:37], v[36:37], v[40:41]
	v_mov_b32_e32 v40, v87
	v_cvt_pk_bf16_f32 v39, v36, v37
	v_pk_mul_f32 v[36:37], v[36:37], v[40:41] op_sel_hi:[1,0]
	s_nop 0
	v_cvt_pk_bf16_f32 v36, v36, v37
	ds_write2_b32 v38, v39, v36 offset0:84 offset1:116
	v_pk_fma_f32 v[36:37], v[32:33], v[82:83], v[22:23]
	v_pk_fma_f32 v[22:23], v[32:33], v[24:25], v[22:23]
	v_pk_fma_f32 v[36:37], v[18:19], v[24:25], v[36:37]
	v_pk_fma_f32 v[18:19], v[18:19], v[28:29], v[22:23]
	v_pk_fma_f32 v[36:37], v[34:35], v[28:29], v[36:37]
	v_pk_fma_f32 v[18:19], v[34:35], v[30:31], v[18:19]
	v_pk_fma_f32 v[36:37], v[20:21], v[30:31], v[36:37]
	v_pk_fma_f32 v[18:19], v[20:21], v[26:27], v[18:19]
	v_pk_mul_f32 v[40:41], v[36:37], s[40:41] op_sel_hi:[1,0]
	v_pk_mul_f32 v[20:21], v[18:19], s[40:41] op_sel_hi:[1,0]
	v_exp_f32_e32 v40, v40
	v_exp_f32_e32 v41, v41
	v_exp_f32_e32 v20, v20
	v_exp_f32_e32 v21, v21
	s_cselect_b64 s[40:41], -1, 0
	v_pk_add_f32 v[40:41], v[40:41], 1.0 op_sel_hi:[1,0]
	s_and_b64 vcc, s[8:9], s[40:41]
	v_rcp_f32_e32 v40, v40
	v_rcp_f32_e32 v41, v41
	v_pk_add_f32 v[20:21], v[20:21], 1.0 op_sel_hi:[1,0]
	v_pk_mul_f32 v[40:41], v[36:37], v[40:41]
	ds_read2_b32 v[36:37], v147 offset0:6 offset1:7
	v_rcp_f32_e32 v20, v20
	v_rcp_f32_e32 v21, v21
	v_cvt_pk_bf16_f32 v39, v40, v41
	s_waitcnt lgkmcnt(0)
	v_pk_mul_f32 v[40:41], v[40:41], v[36:37] op_sel_hi:[1,0]
	v_pk_mul_f32 v[18:19], v[18:19], v[20:21]
	v_mov_b32_e32 v20, v37
	v_cvt_pk_bf16_f32 v21, v18, v19
	v_cvt_pk_bf16_f32 v36, v40, v41
	ds_write2_b32 v38, v39, v36 offset0:152 offset1:184
	v_pk_mul_f32 v[18:19], v[18:19], v[20:21] op_sel_hi:[1,0]
	s_nop 0
	v_cvt_pk_bf16_f32 v18, v18, v19
	ds_write2_b32 v38, v21, v18 offset0:220 offset1:252
	s_cmp_eq_u32 s33, 1
	s_cbranch_scc1 .Lssd_c_first
	s_waitcnt vmcnt(4)
	s_branch .Lssd_c_w

.Lssd_c_w:
	ds_write_b128 v221, v[50:53]
	ds_write_b128 v221, v[54:57] offset:4352
	ds_write_b128 v221, v[58:61] offset:8704
	ds_write_b128 v221, v[62:65] offset:13056
	ds_write_b128 v221, v[66:69] offset:17408
	ds_write_b128 v221, v[70:73] offset:21760
	ds_write_b128 v221, v[74:77] offset:26112
	ds_write_b128 v221, v[78:81] offset:30464
	s_and_saveexec_b64 s[42:43], vcc
	s_cbranch_execz .LBB0_324
	v_readlane_b32 s46, v254, 14
	v_readlane_b32 s47, v254, 15
	s_lshl_b32 s46, s33, 7
	v_mov_b64_e32 v[20:21], s[52:53]
	v_lshl_add_u64 v[18:19], v[130:131], 0, s[46:47]
	s_movk_i32 s37, 0x1e00
	v_mad_u64_u32 v[20:21], vcc, v18, s37, v[20:21]
	v_mad_i32_i24 v21, v19, s37, v21
	s_mov_b32 s37, s47
	v_writelane_b32 v254, s36, 14
	s_nop 1
	v_writelane_b32 v254, s37, 15
	s_mov_b32 s37, s47
	v_lshl_add_u64 v[18:19], v[20:21], 0, s[36:37]
	v_add_co_u32_e32 v20, vcc, 0x1000, v18
	s_nop 1
	v_addc_co_u32_e32 v21, vcc, 0, v19, vcc
	v_add_co_u32_e32 v18, vcc, 0x3000, v18
	s_nop 1
	v_addc_co_u32_e32 v19, vcc, 0, v19, vcc
	global_load_ushort v244, v[20:21], off offset:1024
	global_load_ushort v245, v[18:19], off offset:512
